# adds: grid barrier leader publishes the per-XCD generation (XGEN atomic) before its own L1/L2 acquire invalidate instead of after, so waiting workgroups are released earlier
# speedup vs baseline: 1.0088x; 1.0084x over previous
; DI unsigned xb_ld(unsigned* p) { return __hip_atomic_load(p, __ATOMIC_RELAXED, __HIP_MEMORY_SCOPE_AGENT); }
; DI unsigned xb_add(unsigned* p, unsigned v) { return __hip_atomic_fetch_add(p, v, __ATOMIC_RELAXED, __HIP_MEMORY_SCOPE_AGENT); }
; #define XB_SPIN(cond, bar) do { unsigned _sp = 0; while (cond) { __builtin_amdgcn_s_sleep(1); \
;     if ((++_sp & 255u) == 0u) { if (xb_ld(&(bar)[XB_TMO])) break; if (_sp > XB_SPIN_CAP) { atomicAdd(&(bar)[XB_TMO], 1u); break; } } } } while (0)
; DI void xcd_barrier(unsigned* bar, volatile LAS unsigned* st) {
;     ...
;       else XB_SPIN(xb_ld(&bar[XB_TOPGEN]) == tg, bar);
;       __builtin_amdgcn_fence(__ATOMIC_ACQUIRE, "agent");
;       xb_add(&bar[XB_XGEN(x)], 1u);
;       asm volatile("s_waitcnt vmcnt(0)" ::: "memory");
.LBB0_320:
	s_or_b64 exec, exec, s[0:1]
	v_mov_b32_e32 v0, s3
	v_add_co_u32_e32 v2, vcc, 0x2000, v0
	v_mov_b32_e32 v0, s2
	s_nop 0
	v_addc_co_u32_e32 v3, vcc, 0, v0, vcc
	s_waitcnt vmcnt(0) lgkmcnt(0)
	flat_atomic_add v[2:3], v187 offset:1024
	buffer_inv sc1
	s_waitcnt vmcnt(0)

; DI unsigned xb_ld(unsigned* p) { return __hip_atomic_load(p, __ATOMIC_RELAXED, __HIP_MEMORY_SCOPE_AGENT); }
; DI unsigned xb_add(unsigned* p, unsigned v) { return __hip_atomic_fetch_add(p, v, __ATOMIC_RELAXED, __HIP_MEMORY_SCOPE_AGENT); }
; #define XB_SPIN(cond, bar) do { unsigned _sp = 0; while (cond) { __builtin_amdgcn_s_sleep(1); \
;     if ((++_sp & 255u) == 0u) { if (xb_ld(&(bar)[XB_TMO])) break; if (_sp > XB_SPIN_CAP) { atomicAdd(&(bar)[XB_TMO], 1u); break; } } } } while (0)
; DI void xcd_barrier(unsigned* bar, volatile LAS unsigned* st) {
;     ...
;       else XB_SPIN(xb_ld(&bar[XB_TOPGEN]) == tg, bar);
;       __builtin_amdgcn_fence(__ATOMIC_ACQUIRE, "agent");
;       xb_add(&bar[XB_XGEN(x)], 1u);
;       asm volatile("s_waitcnt vmcnt(0)" ::: "memory");
.LBB0_378:
	s_or_b64 exec, exec, s[0:1]
	v_mov_b32_e32 v0, s25
	v_add_co_u32_e32 v2, vcc, 0x2000, v0
	v_mov_b32_e32 v0, s24
	s_nop 0
	v_addc_co_u32_e32 v3, vcc, 0, v0, vcc
	s_waitcnt vmcnt(0) lgkmcnt(0)
	flat_atomic_add v[2:3], v187 offset:1024
	buffer_inv sc1
	s_waitcnt vmcnt(0)

; DI unsigned xb_ld(unsigned* p) { return __hip_atomic_load(p, __ATOMIC_RELAXED, __HIP_MEMORY_SCOPE_AGENT); }
; DI unsigned xb_add(unsigned* p, unsigned v) { return __hip_atomic_fetch_add(p, v, __ATOMIC_RELAXED, __HIP_MEMORY_SCOPE_AGENT); }
; #define XB_SPIN(cond, bar) do { unsigned _sp = 0; while (cond) { __builtin_amdgcn_s_sleep(1); \
;     if ((++_sp & 255u) == 0u) { if (xb_ld(&(bar)[XB_TMO])) break; if (_sp > XB_SPIN_CAP) { atomicAdd(&(bar)[XB_TMO], 1u); break; } } } } while (0)
; DI void xcd_barrier(unsigned* bar, volatile LAS unsigned* st) {
;     ...
;       else XB_SPIN(xb_ld(&bar[XB_TOPGEN]) == tg, bar);
;       __builtin_amdgcn_fence(__ATOMIC_ACQUIRE, "agent");
;       xb_add(&bar[XB_XGEN(x)], 1u);
;       asm volatile("s_waitcnt vmcnt(0)" ::: "memory");
.LBB0_572:
	s_or_b64 exec, exec, s[0:1]
	v_mov_b32_e32 v0, s24
	v_add_co_u32_e32 v2, vcc, 0x2000, v0
	v_mov_b32_e32 v0, s3
	s_nop 0
	v_addc_co_u32_e32 v3, vcc, 0, v0, vcc
	s_waitcnt vmcnt(0) lgkmcnt(0)
	flat_atomic_add v[2:3], v187 offset:1024
	buffer_inv sc1
	s_waitcnt vmcnt(0)
